# WIN and UP K-loops: first k-tile pair peeled with C=0 MFMAs, accumulator zeroing blocks removed
# speedup vs baseline: 1.0070x; 1.0070x over previous
.LBB0_309:
	s_mul_i32 s3, s74, 0x8400
	v_readlane_b32 s48, v252, 45
	s_ashr_i32 s4, s3, 31
	v_readlane_b32 s60, v252, 57
	v_readlane_b32 s61, v252, 58
	s_add_u32 s30, s60, s3
	s_addc_u32 s31, s61, s4
	s_mov_b64 s[4:5], 0x80
	v_readlane_b32 s50, v252, 47
	s_lshl_b32 s1, s1, 5
	v_lshl_add_u64 v[8:9], v[8:9], 0, s[4:5]
	s_add_i32 m0, s15, 0x18000
	v_readlane_b32 s51, v252, 48
	s_and_b32 s44, s1, 0x60
	s_waitcnt vmcnt(2)
	s_barrier
	global_load_lds_dwordx4 v[8:9], off
	v_lshl_add_u64 v[6:7], v[6:7], 0, s[4:5]
	s_add_i32 m0, s15, 0x1a000
	s_add_i32 s50, s15, 0x8000
	s_lshl_b32 s41, s0, 6
	s_lshl_b32 s3, s0, 13
	s_lshl_b32 s1, s44, 7
	global_load_lds_dwordx4 v[6:7], off
	v_lshl_add_u64 v[2:3], v[2:3], 0, s[4:5]
	s_mov_b32 m0, s50
	s_add_i32 s51, s15, 0xa000
	global_load_lds_dwordx4 v[2:3], off
	v_lshl_add_u64 v[2:3], v[4:5], 0, s[4:5]
	s_add_u32 s4, s26, 0x40080
	s_mov_b32 m0, s51
	s_addc_u32 s5, s27, 0
	global_load_lds_dwordx4 v[2:3], off
	v_lshl_add_u64 v[2:3], s[4:5], 0, v[170:171]
	s_add_i32 m0, s15, 0x1c000
	v_bfe_u32 v189, v10, 4, 2
	global_load_lds_dwordx4 v[2:3], off
	v_lshl_add_u64 v[2:3], s[4:5], 0, v[172:173]
	s_add_i32 m0, s15, 0x1e000
	v_and_b32_e32 v188, 15, v10
	global_load_lds_dwordx4 v[2:3], off
	v_lshlrev_b32_e32 v13, 4, v189
	v_lshlrev_b32_e32 v10, 2, v10
	v_lshl_or_b32 v13, v188, 6, v13
	v_and_b32_e32 v10, 32, v10
	s_cmpk_lt_u32 s2, 0x100
	v_bitop3_b32 v190, v13, s1, v10 bitop3:0xde
	s_cselect_b64 s[36:37], -1, 0
	s_lshl_b32 s1, s0, 10
	s_cmp_gt_i32 s0, 0
	s_cselect_b64 s[38:39], -1, 0
	s_cmp_gt_i32 s0, -2
	s_mul_i32 s0, s74, 0x2600000
	s_cselect_b64 s[46:47], -1, 0
	s_ashr_i32 s2, s0, 31
	s_add_u32 s0, s82, s0
	v_readlane_b32 s62, v252, 59
	s_addc_u32 s2, s83, s2
	v_readlane_b32 s63, v252, 60
	s_add_u32 s62, s0, 0x1680000
	v_bitop3_b32 v14, v13, s3, v10 bitop3:0xde
	s_addc_u32 s63, s2, 0
	v_readlane_b32 s2, v253, 25
	s_mov_b32 s4, s2
	s_mul_hi_i32 s0, s2, 0x180000
	s_mul_i32 s2, s2, 0x180000
	v_readlane_b32 s3, v253, 26
	s_add_u32 s2, s82, s2
	s_addc_u32 s0, s83, s0
	s_mul_hi_i32 s3, s4, 0xffea0000
	s_mul_i32 s4, s4, 0xffea0000
	s_add_u32 s2, s2, s4
	s_addc_u32 s0, s0, s3
	s_add_u32 s64, s2, 0x15000000
	s_addc_u32 s65, s0, 0
	v_lshlrev_b32_e32 v2, 14, v0
	v_readlane_b32 s49, v252, 46
	s_add_u32 s48, s82, 0x1f000000
	v_and_b32_e32 v2, 0xffff8000, v2
	s_addc_u32 s49, s83, 0
	v_and_b32_e32 v0, 1, v0
	v_lshl_add_u32 v2, v11, 11, v2
	s_waitcnt vmcnt(6)
	s_add_u32 s10, s82, 0x1f160000
	v_lshl_or_b32 v0, v0, 6, v2
	s_addc_u32 s11, s83, 0
	s_add_i32 s67, s1, 0
	v_lshl_add_u32 v178, v12, 1, v0
	v_readlane_b32 s52, v252, 49
	v_readlane_b32 s53, v252, 50
	v_readlane_b32 s54, v252, 51
	s_mov_b32 s69, 0
	s_add_i32 s66, s67, 0x21c00
	s_add_i32 s67, s67, 0x21800
	v_add_u32_e32 v180, 0x20000, v178
	v_mov_b32_e32 v181, v1
	v_mov_b32_e32 v179, v1
	v_add_u32_e32 v191, 0, v14
	v_readlane_b32 s55, v252, 52
	v_readlane_b32 s56, v252, 53
	v_readlane_b32 s57, v252, 54
	v_readlane_b32 s58, v252, 55
	v_readlane_b32 s59, v252, 56
	s_barrier
	s_branch .LBB0_314

.LBB0_313:
	s_mov_b64 s[34:35], s[58:59]
	s_mov_b32 s69, s70
	s_andn2_b64 vcc, exec, s[56:57]
	s_cbranch_vccz .LBB0_338
.LBB0_314:
	s_add_u32 s71, s26, 0x100
	s_addc_u32 s72, s27, 0
	s_add_i32 s70, s69, 1
	s_lshl_b32 s0, s70, 2
	v_readlane_b32 s2, v253, 22
	s_add_i32 s0, s0, s2
	s_cmp_lt_i32 s0, 22
	s_cselect_b64 s[60:61], -1, 0
	s_cmp_gt_i32 s0, 21
	s_cselect_b64 s[56:57], -1, 0
	s_ashr_i32 s1, s0, 31
	s_lshl_b64 s[0:1], s[0:1], 19
	v_readlane_b32 s3, v253, 23
	s_add_u32 s2, s62, s0
	s_addc_u32 s3, s63, s1
	s_and_b64 s[0:1], s[60:61], exec
	s_cselect_b32 s27, s3, s27
	s_cselect_b32 s26, s2, s26
	s_cselect_b32 s59, s25, s35
	s_cselect_b32 s58, s24, s34
	s_add_u32 s0, s34, 0x40080
	s_addc_u32 s1, s35, 0
	v_lshl_add_u64 v[130:131], s[0:1], 0, v[180:181]
	v_lshl_add_u64 v[132:133], s[0:1], 0, v[178:179]
	s_mov_b32 s6, -2
	s_mov_b64 s[0:1], 0
	s_mov_b64 s[42:43], 0x80
	s_add_u32 s2, s34, s0
	s_addc_u32 s3, s35, s1
	s_add_u32 s2, s2, 0x100
	s_addc_u32 s3, s3, 0
	s_add_u32 s7, s71, s0
	s_addc_u32 s8, s72, s1
	s_add_i32 s9, 0, 0x10000
	s_cmpk_eq_i32 s0, 0x700
	s_cselect_b32 s5, s59, s3
	s_cselect_b32 s4, s58, s2
	v_add_u32_e32 v0, s9, v190
	s_cselect_b32 s3, s27, s8
	s_cselect_b32 s2, s26, s7
	s_add_i32 s7, 0, 0x14000
	ds_read_b128 v[134:137], v0
	ds_read_b128 v[138:141], v0 offset:1024
	ds_read_b128 v[142:145], v0 offset:2048
	ds_read_b128 v[146:149], v0 offset:3072
	v_add_u32_e32 v0, s7, v190
	ds_read_b128 v[150:153], v0
	ds_read_b128 v[154:157], v0 offset:1024
	ds_read_b128 v[158:161], v0 offset:2048
	ds_read_b128 v[162:165], v0 offset:3072
	v_lshl_add_u64 v[186:187], v[132:133], 0, s[0:1]
	s_add_i32 m0, s15, 0xc000
	ds_read_b128 v[166:169], v191
	ds_read_b128 v[182:185], v191 offset:1024
	ds_read_b128 v[192:195], v191 offset:2048
	ds_read_b128 v[196:199], v191 offset:3072
	ds_read_b128 v[200:203], v191 offset:4096
	ds_read_b128 v[204:207], v191 offset:5120
	ds_read_b128 v[208:211], v191 offset:6144
	ds_read_b128 v[212:215], v191 offset:7168
	global_load_lds_dwordx4 v[186:187], off
	v_lshl_add_u64 v[186:187], v[130:131], 0, s[0:1]
	s_add_i32 m0, s15, 0xe000
	s_nop 0
	global_load_lds_dwordx4 v[186:187], off
	s_waitcnt vmcnt(8)
	s_waitcnt lgkmcnt(0)
	s_barrier
	s_setprio 1
	v_mfma_f32_16x16x32_bf16 v[126:129], v[134:137], v[166:169], 0
	v_mfma_f32_16x16x32_bf16 v[122:125], v[142:145], v[166:169], 0
	v_mfma_f32_16x16x32_bf16 v[118:121], v[134:137], v[192:195], 0
	v_mfma_f32_16x16x32_bf16 v[114:117], v[142:145], v[192:195], 0
	v_mfma_f32_16x16x32_bf16 v[110:113], v[134:137], v[200:203], 0
	v_mfma_f32_16x16x32_bf16 v[106:109], v[142:145], v[200:203], 0
	v_mfma_f32_16x16x32_bf16 v[102:105], v[134:137], v[208:211], 0
	v_mfma_f32_16x16x32_bf16 v[98:101], v[142:145], v[208:211], 0
	v_mfma_f32_16x16x32_bf16 v[126:129], v[138:141], v[182:185], v[126:129]
	v_mfma_f32_16x16x32_bf16 v[122:125], v[146:149], v[182:185], v[122:125]
	v_mfma_f32_16x16x32_bf16 v[118:121], v[138:141], v[196:199], v[118:121]
	v_mfma_f32_16x16x32_bf16 v[114:117], v[146:149], v[196:199], v[114:117]
	v_mfma_f32_16x16x32_bf16 v[110:113], v[138:141], v[204:207], v[110:113]
	v_mfma_f32_16x16x32_bf16 v[106:109], v[146:149], v[204:207], v[106:109]
	v_mfma_f32_16x16x32_bf16 v[102:105], v[138:141], v[212:215], v[102:105]
	v_mfma_f32_16x16x32_bf16 v[98:101], v[146:149], v[212:215], v[98:101]
	v_mfma_f32_16x16x32_bf16 v[94:97], v[150:153], v[166:169], 0
	v_mfma_f32_16x16x32_bf16 v[90:93], v[158:161], v[166:169], 0
	v_mfma_f32_16x16x32_bf16 v[86:89], v[150:153], v[192:195], 0
	v_mfma_f32_16x16x32_bf16 v[82:85], v[158:161], v[192:195], 0
	v_mfma_f32_16x16x32_bf16 v[78:81], v[150:153], v[200:203], 0
	v_mfma_f32_16x16x32_bf16 v[74:77], v[158:161], v[200:203], 0
	v_mfma_f32_16x16x32_bf16 v[70:73], v[150:153], v[208:211], 0
	v_mfma_f32_16x16x32_bf16 v[66:69], v[158:161], v[208:211], 0
	v_mfma_f32_16x16x32_bf16 v[94:97], v[154:157], v[182:185], v[94:97]
	v_mfma_f32_16x16x32_bf16 v[90:93], v[162:165], v[182:185], v[90:93]
	v_mfma_f32_16x16x32_bf16 v[86:89], v[154:157], v[196:199], v[86:89]
	v_mfma_f32_16x16x32_bf16 v[82:85], v[162:165], v[196:199], v[82:85]
	v_mfma_f32_16x16x32_bf16 v[78:81], v[154:157], v[204:207], v[78:81]
	v_mfma_f32_16x16x32_bf16 v[74:77], v[162:165], v[204:207], v[74:77]
	v_mfma_f32_16x16x32_bf16 v[70:73], v[154:157], v[212:215], v[70:73]
	v_mfma_f32_16x16x32_bf16 v[66:69], v[162:165], v[212:215], v[66:69]
	s_setprio 0
	s_barrier
	s_add_i32 s8, s9, s14
	v_lshl_add_u64 v[186:187], s[2:3], 0, v[170:171]
	s_mov_b32 m0, s8
	ds_read_b128 v[166:169], v191 offset:16384
	ds_read_b128 v[182:185], v191 offset:17408
	ds_read_b128 v[192:195], v191 offset:18432
	ds_read_b128 v[196:199], v191 offset:19456
	ds_read_b128 v[200:203], v191 offset:20480
	ds_read_b128 v[204:207], v191 offset:21504
	ds_read_b128 v[208:211], v191 offset:22528
	ds_read_b128 v[212:215], v191 offset:23552
	global_load_lds_dwordx4 v[186:187], off
	s_add_i32 m0, s8, 0x2000
	s_add_u32 s8, s2, 0x40000
	v_lshl_add_u64 v[236:237], s[2:3], 0, v[172:173]
	s_addc_u32 s9, s3, 0
	s_add_i32 s7, s7, s14
	global_load_lds_dwordx4 v[236:237], off
	v_lshl_add_u64 v[238:239], s[8:9], 0, v[170:171]
	s_mov_b32 m0, s7
	v_lshl_add_u64 v[244:245], s[4:5], 0, v[176:177]
	global_load_lds_dwordx4 v[238:239], off
	v_lshl_add_u64 v[238:239], s[8:9], 0, v[172:173]
	s_add_i32 m0, s7, 0x2000
	s_nop 0
	global_load_lds_dwordx4 v[238:239], off
	v_lshl_add_u64 v[238:239], s[4:5], 0, v[174:175]
	s_mov_b32 m0, s15
	s_nop 0
	global_load_lds_dwordx4 v[238:239], off
	s_mov_b32 m0, s17
	s_nop 0
	global_load_lds_dwordx4 v[244:245], off
	s_waitcnt vmcnt(8)
	s_waitcnt lgkmcnt(0)
	s_barrier
	s_setprio 1
	v_mfma_f32_16x16x32_bf16 v[62:65], v[134:137], v[166:169], 0
	v_mfma_f32_16x16x32_bf16 v[58:61], v[142:145], v[166:169], 0
	v_mfma_f32_16x16x32_bf16 v[54:57], v[134:137], v[192:195], 0
	v_mfma_f32_16x16x32_bf16 v[50:53], v[142:145], v[192:195], 0
	v_mfma_f32_16x16x32_bf16 v[46:49], v[134:137], v[200:203], 0
	v_mfma_f32_16x16x32_bf16 v[42:45], v[142:145], v[200:203], 0
	v_mfma_f32_16x16x32_bf16 v[38:41], v[134:137], v[208:211], 0
	v_mfma_f32_16x16x32_bf16 v[34:37], v[142:145], v[208:211], 0
	v_mfma_f32_16x16x32_bf16 v[62:65], v[138:141], v[182:185], v[62:65]
	v_mfma_f32_16x16x32_bf16 v[58:61], v[146:149], v[182:185], v[58:61]
	v_mfma_f32_16x16x32_bf16 v[54:57], v[138:141], v[196:199], v[54:57]
	v_mfma_f32_16x16x32_bf16 v[50:53], v[146:149], v[196:199], v[50:53]
	v_mfma_f32_16x16x32_bf16 v[46:49], v[138:141], v[204:207], v[46:49]
	v_mfma_f32_16x16x32_bf16 v[42:45], v[146:149], v[204:207], v[42:45]
	v_mfma_f32_16x16x32_bf16 v[38:41], v[138:141], v[212:215], v[38:41]
	v_mfma_f32_16x16x32_bf16 v[34:37], v[146:149], v[212:215], v[34:37]
	v_mfma_f32_16x16x32_bf16 v[30:33], v[150:153], v[166:169], 0
	v_mfma_f32_16x16x32_bf16 v[26:29], v[158:161], v[166:169], 0
	v_mfma_f32_16x16x32_bf16 v[22:25], v[150:153], v[192:195], 0
	v_mfma_f32_16x16x32_bf16 v[18:21], v[158:161], v[192:195], 0
	v_mfma_f32_16x16x32_bf16 v[14:17], v[150:153], v[200:203], 0
	v_mfma_f32_16x16x32_bf16 v[10:13], v[158:161], v[200:203], 0
	v_mfma_f32_16x16x32_bf16 v[6:9], v[150:153], v[208:211], 0
	v_mfma_f32_16x16x32_bf16 v[2:5], v[158:161], v[208:211], 0
	v_mfma_f32_16x16x32_bf16 v[30:33], v[154:157], v[182:185], v[30:33]
	v_mfma_f32_16x16x32_bf16 v[26:29], v[162:165], v[182:185], v[26:29]
	v_mfma_f32_16x16x32_bf16 v[22:25], v[154:157], v[196:199], v[22:25]
	v_mfma_f32_16x16x32_bf16 v[18:21], v[162:165], v[196:199], v[18:21]
	v_mfma_f32_16x16x32_bf16 v[14:17], v[154:157], v[204:207], v[14:17]
	v_mfma_f32_16x16x32_bf16 v[10:13], v[162:165], v[204:207], v[10:13]
	v_mfma_f32_16x16x32_bf16 v[6:9], v[154:157], v[212:215], v[6:9]
	v_mfma_f32_16x16x32_bf16 v[2:5], v[162:165], v[212:215], v[2:5]
	s_setprio 0
	s_barrier
	s_add_i32 s7, 0, 0x18000
	v_add_u32_e32 v0, s7, v190
	s_add_i32 s8, 0, 0x1c000
	ds_read_b128 v[134:137], v0
	ds_read_b128 v[138:141], v0 offset:1024
	ds_read_b128 v[142:145], v0 offset:2048
	ds_read_b128 v[146:149], v0 offset:3072
	v_add_u32_e32 v0, s8, v190
	ds_read_b128 v[150:153], v0
	ds_read_b128 v[154:157], v0 offset:1024
	ds_read_b128 v[158:161], v0 offset:2048
	ds_read_b128 v[162:165], v0 offset:3072
	s_add_u32 s4, s4, 0x40000
	s_addc_u32 s5, s5, 0
	s_mov_b32 m0, s19
	v_lshl_add_u64 v[246:247], s[4:5], 0, v[174:175]
	ds_read_b128 v[166:169], v191 offset:32768
	ds_read_b128 v[182:185], v191 offset:33792
	ds_read_b128 v[192:195], v191 offset:34816
	ds_read_b128 v[196:199], v191 offset:35840
	ds_read_b128 v[200:203], v191 offset:36864
	ds_read_b128 v[204:207], v191 offset:37888
	ds_read_b128 v[208:211], v191 offset:38912
	ds_read_b128 v[212:215], v191 offset:39936
	global_load_lds_dwordx4 v[246:247], off
	v_lshl_add_u64 v[246:247], s[4:5], 0, v[176:177]
	s_mov_b32 m0, s40
	s_nop 0
	global_load_lds_dwordx4 v[246:247], off
	s_waitcnt vmcnt(8)
	s_waitcnt lgkmcnt(0)
	s_barrier
	s_setprio 1
	v_mfma_f32_16x16x32_bf16 v[126:129], v[134:137], v[166:169], v[126:129]
	v_mfma_f32_16x16x32_bf16 v[122:125], v[142:145], v[166:169], v[122:125]
	v_mfma_f32_16x16x32_bf16 v[118:121], v[134:137], v[192:195], v[118:121]
	v_mfma_f32_16x16x32_bf16 v[114:117], v[142:145], v[192:195], v[114:117]
	v_mfma_f32_16x16x32_bf16 v[110:113], v[134:137], v[200:203], v[110:113]
	v_mfma_f32_16x16x32_bf16 v[106:109], v[142:145], v[200:203], v[106:109]
	v_mfma_f32_16x16x32_bf16 v[102:105], v[134:137], v[208:211], v[102:105]
	v_mfma_f32_16x16x32_bf16 v[98:101], v[142:145], v[208:211], v[98:101]
	v_mfma_f32_16x16x32_bf16 v[126:129], v[138:141], v[182:185], v[126:129]
	v_mfma_f32_16x16x32_bf16 v[122:125], v[146:149], v[182:185], v[122:125]
	v_mfma_f32_16x16x32_bf16 v[118:121], v[138:141], v[196:199], v[118:121]
	v_mfma_f32_16x16x32_bf16 v[114:117], v[146:149], v[196:199], v[114:117]
	v_mfma_f32_16x16x32_bf16 v[110:113], v[138:141], v[204:207], v[110:113]
	v_mfma_f32_16x16x32_bf16 v[106:109], v[146:149], v[204:207], v[106:109]
	v_mfma_f32_16x16x32_bf16 v[102:105], v[138:141], v[212:215], v[102:105]
	v_mfma_f32_16x16x32_bf16 v[98:101], v[146:149], v[212:215], v[98:101]
	v_mfma_f32_16x16x32_bf16 v[94:97], v[150:153], v[166:169], v[94:97]
	v_mfma_f32_16x16x32_bf16 v[90:93], v[158:161], v[166:169], v[90:93]
	v_mfma_f32_16x16x32_bf16 v[86:89], v[150:153], v[192:195], v[86:89]
	v_mfma_f32_16x16x32_bf16 v[82:85], v[158:161], v[192:195], v[82:85]
	v_mfma_f32_16x16x32_bf16 v[78:81], v[150:153], v[200:203], v[78:81]
	v_mfma_f32_16x16x32_bf16 v[74:77], v[158:161], v[200:203], v[74:77]
	v_mfma_f32_16x16x32_bf16 v[70:73], v[150:153], v[208:211], v[70:73]
	v_mfma_f32_16x16x32_bf16 v[66:69], v[158:161], v[208:211], v[66:69]
	v_mfma_f32_16x16x32_bf16 v[94:97], v[154:157], v[182:185], v[94:97]
	v_mfma_f32_16x16x32_bf16 v[90:93], v[162:165], v[182:185], v[90:93]
	v_mfma_f32_16x16x32_bf16 v[86:89], v[154:157], v[196:199], v[86:89]
	v_mfma_f32_16x16x32_bf16 v[82:85], v[162:165], v[196:199], v[82:85]
	v_mfma_f32_16x16x32_bf16 v[78:81], v[154:157], v[204:207], v[78:81]
	v_mfma_f32_16x16x32_bf16 v[74:77], v[162:165], v[204:207], v[74:77]
	v_mfma_f32_16x16x32_bf16 v[70:73], v[154:157], v[212:215], v[70:73]
	v_mfma_f32_16x16x32_bf16 v[66:69], v[162:165], v[212:215], v[66:69]
	s_setprio 0
	s_barrier
	s_add_i32 s4, s7, s14
	v_lshl_add_u64 v[186:187], v[186:187], 0, s[42:43]
	s_mov_b32 m0, s4
	ds_read_b128 v[166:169], v191 offset:49152
	ds_read_b128 v[182:185], v191 offset:50176
	ds_read_b128 v[192:195], v191 offset:51200
	ds_read_b128 v[196:199], v191 offset:52224
	ds_read_b128 v[200:203], v191 offset:53248
	ds_read_b128 v[204:207], v191 offset:54272
	ds_read_b128 v[208:211], v191 offset:55296
	ds_read_b128 v[212:215], v191 offset:56320
	global_load_lds_dwordx4 v[186:187], off
	s_add_i32 m0, s4, 0x2000
	s_add_u32 s2, s2, 0x40080
	v_lshl_add_u64 v[186:187], v[236:237], 0, s[42:43]
	s_addc_u32 s3, s3, 0
	s_add_i32 s4, s8, s14
	global_load_lds_dwordx4 v[186:187], off
	v_lshl_add_u64 v[186:187], s[2:3], 0, v[170:171]
	s_mov_b32 m0, s4
	s_nop 0
	global_load_lds_dwordx4 v[186:187], off
	v_lshl_add_u64 v[186:187], s[2:3], 0, v[172:173]
	s_add_i32 m0, s4, 0x2000
	s_nop 0
	global_load_lds_dwordx4 v[186:187], off
	v_lshl_add_u64 v[186:187], v[238:239], 0, s[42:43]
	s_mov_b32 m0, s50
	s_nop 0
	global_load_lds_dwordx4 v[186:187], off
	v_lshl_add_u64 v[186:187], v[244:245], 0, s[42:43]
	s_mov_b32 m0, s51
	s_nop 0
	global_load_lds_dwordx4 v[186:187], off
	s_waitcnt vmcnt(8)
	s_waitcnt lgkmcnt(0)
	s_barrier
	s_setprio 1
	v_mfma_f32_16x16x32_bf16 v[62:65], v[134:137], v[166:169], v[62:65]
	v_mfma_f32_16x16x32_bf16 v[58:61], v[142:145], v[166:169], v[58:61]
	v_mfma_f32_16x16x32_bf16 v[54:57], v[134:137], v[192:195], v[54:57]
	v_mfma_f32_16x16x32_bf16 v[50:53], v[142:145], v[192:195], v[50:53]
	v_mfma_f32_16x16x32_bf16 v[46:49], v[134:137], v[200:203], v[46:49]
	v_mfma_f32_16x16x32_bf16 v[42:45], v[142:145], v[200:203], v[42:45]
	v_mfma_f32_16x16x32_bf16 v[38:41], v[134:137], v[208:211], v[38:41]
	v_mfma_f32_16x16x32_bf16 v[34:37], v[142:145], v[208:211], v[34:37]
	v_mfma_f32_16x16x32_bf16 v[62:65], v[138:141], v[182:185], v[62:65]
	v_mfma_f32_16x16x32_bf16 v[58:61], v[146:149], v[182:185], v[58:61]
	v_mfma_f32_16x16x32_bf16 v[54:57], v[138:141], v[196:199], v[54:57]
	v_mfma_f32_16x16x32_bf16 v[50:53], v[146:149], v[196:199], v[50:53]
	v_mfma_f32_16x16x32_bf16 v[46:49], v[138:141], v[204:207], v[46:49]
	v_mfma_f32_16x16x32_bf16 v[42:45], v[146:149], v[204:207], v[42:45]
	v_mfma_f32_16x16x32_bf16 v[38:41], v[138:141], v[212:215], v[38:41]
	v_mfma_f32_16x16x32_bf16 v[34:37], v[146:149], v[212:215], v[34:37]
	v_mfma_f32_16x16x32_bf16 v[30:33], v[150:153], v[166:169], v[30:33]
	v_mfma_f32_16x16x32_bf16 v[26:29], v[158:161], v[166:169], v[26:29]
	v_mfma_f32_16x16x32_bf16 v[22:25], v[150:153], v[192:195], v[22:25]
	v_mfma_f32_16x16x32_bf16 v[18:21], v[158:161], v[192:195], v[18:21]
	v_mfma_f32_16x16x32_bf16 v[14:17], v[150:153], v[200:203], v[14:17]
	v_mfma_f32_16x16x32_bf16 v[10:13], v[158:161], v[200:203], v[10:13]
	v_mfma_f32_16x16x32_bf16 v[6:9], v[150:153], v[208:211], v[6:9]
	v_mfma_f32_16x16x32_bf16 v[2:5], v[158:161], v[208:211], v[2:5]
	v_mfma_f32_16x16x32_bf16 v[30:33], v[154:157], v[182:185], v[30:33]
	v_mfma_f32_16x16x32_bf16 v[26:29], v[162:165], v[182:185], v[26:29]
	v_mfma_f32_16x16x32_bf16 v[22:25], v[154:157], v[196:199], v[22:25]
	v_mfma_f32_16x16x32_bf16 v[18:21], v[162:165], v[196:199], v[18:21]
	v_mfma_f32_16x16x32_bf16 v[14:17], v[154:157], v[204:207], v[14:17]
	v_mfma_f32_16x16x32_bf16 v[10:13], v[162:165], v[204:207], v[10:13]
	v_mfma_f32_16x16x32_bf16 v[6:9], v[154:157], v[212:215], v[6:9]
	v_mfma_f32_16x16x32_bf16 v[2:5], v[162:165], v[212:215], v[2:5]
	s_setprio 0
	s_barrier
	s_add_i32 s6, s6, 2
	s_add_u32 s0, s0, 0x100
	s_addc_u32 s1, s1, 0
	s_cmp_gt_u32 s6, 13
	s_cbranch_scc1 .Lkp_exit_up
.LBB0_315:
	s_add_u32 s2, s34, s0
	s_addc_u32 s3, s35, s1
	s_add_u32 s2, s2, 0x100
	s_addc_u32 s3, s3, 0
	s_add_u32 s7, s71, s0
	s_addc_u32 s8, s72, s1
	s_add_i32 s9, 0, 0x10000
	s_cmpk_eq_i32 s0, 0x700
	s_cselect_b32 s5, s59, s3
	s_cselect_b32 s4, s58, s2
	v_add_u32_e32 v0, s9, v190
	s_cselect_b32 s3, s27, s8
	s_cselect_b32 s2, s26, s7
	s_add_i32 s7, 0, 0x14000
	ds_read_b128 v[134:137], v0
	ds_read_b128 v[138:141], v0 offset:1024
	ds_read_b128 v[142:145], v0 offset:2048
	ds_read_b128 v[146:149], v0 offset:3072
	v_add_u32_e32 v0, s7, v190
	ds_read_b128 v[150:153], v0
	ds_read_b128 v[154:157], v0 offset:1024
	ds_read_b128 v[158:161], v0 offset:2048
	ds_read_b128 v[162:165], v0 offset:3072
	v_lshl_add_u64 v[186:187], v[132:133], 0, s[0:1]
	s_add_i32 m0, s15, 0xc000
	ds_read_b128 v[166:169], v191
	ds_read_b128 v[182:185], v191 offset:1024
	ds_read_b128 v[192:195], v191 offset:2048
	ds_read_b128 v[196:199], v191 offset:3072
	ds_read_b128 v[200:203], v191 offset:4096
	ds_read_b128 v[204:207], v191 offset:5120
	ds_read_b128 v[208:211], v191 offset:6144
	ds_read_b128 v[212:215], v191 offset:7168
	global_load_lds_dwordx4 v[186:187], off
	v_lshl_add_u64 v[186:187], v[130:131], 0, s[0:1]
	s_add_i32 m0, s15, 0xe000
	s_nop 0
	global_load_lds_dwordx4 v[186:187], off
	s_waitcnt vmcnt(8)
	s_waitcnt lgkmcnt(0)
	s_barrier
	s_setprio 1
	v_mfma_f32_16x16x32_bf16 v[126:129], v[134:137], v[166:169], v[126:129]
	v_mfma_f32_16x16x32_bf16 v[122:125], v[142:145], v[166:169], v[122:125]
	v_mfma_f32_16x16x32_bf16 v[118:121], v[134:137], v[192:195], v[118:121]
	v_mfma_f32_16x16x32_bf16 v[114:117], v[142:145], v[192:195], v[114:117]
	v_mfma_f32_16x16x32_bf16 v[110:113], v[134:137], v[200:203], v[110:113]
	v_mfma_f32_16x16x32_bf16 v[106:109], v[142:145], v[200:203], v[106:109]
	v_mfma_f32_16x16x32_bf16 v[102:105], v[134:137], v[208:211], v[102:105]
	v_mfma_f32_16x16x32_bf16 v[98:101], v[142:145], v[208:211], v[98:101]
	v_mfma_f32_16x16x32_bf16 v[126:129], v[138:141], v[182:185], v[126:129]
	v_mfma_f32_16x16x32_bf16 v[122:125], v[146:149], v[182:185], v[122:125]
	v_mfma_f32_16x16x32_bf16 v[118:121], v[138:141], v[196:199], v[118:121]
	v_mfma_f32_16x16x32_bf16 v[114:117], v[146:149], v[196:199], v[114:117]
	v_mfma_f32_16x16x32_bf16 v[110:113], v[138:141], v[204:207], v[110:113]
	v_mfma_f32_16x16x32_bf16 v[106:109], v[146:149], v[204:207], v[106:109]
	v_mfma_f32_16x16x32_bf16 v[102:105], v[138:141], v[212:215], v[102:105]
	v_mfma_f32_16x16x32_bf16 v[98:101], v[146:149], v[212:215], v[98:101]
	v_mfma_f32_16x16x32_bf16 v[94:97], v[150:153], v[166:169], v[94:97]
	v_mfma_f32_16x16x32_bf16 v[90:93], v[158:161], v[166:169], v[90:93]
	v_mfma_f32_16x16x32_bf16 v[86:89], v[150:153], v[192:195], v[86:89]
	v_mfma_f32_16x16x32_bf16 v[82:85], v[158:161], v[192:195], v[82:85]
	v_mfma_f32_16x16x32_bf16 v[78:81], v[150:153], v[200:203], v[78:81]
	v_mfma_f32_16x16x32_bf16 v[74:77], v[158:161], v[200:203], v[74:77]
	v_mfma_f32_16x16x32_bf16 v[70:73], v[150:153], v[208:211], v[70:73]
	v_mfma_f32_16x16x32_bf16 v[66:69], v[158:161], v[208:211], v[66:69]
	v_mfma_f32_16x16x32_bf16 v[94:97], v[154:157], v[182:185], v[94:97]
	v_mfma_f32_16x16x32_bf16 v[90:93], v[162:165], v[182:185], v[90:93]
	v_mfma_f32_16x16x32_bf16 v[86:89], v[154:157], v[196:199], v[86:89]
	v_mfma_f32_16x16x32_bf16 v[82:85], v[162:165], v[196:199], v[82:85]
	v_mfma_f32_16x16x32_bf16 v[78:81], v[154:157], v[204:207], v[78:81]
	v_mfma_f32_16x16x32_bf16 v[74:77], v[162:165], v[204:207], v[74:77]
	v_mfma_f32_16x16x32_bf16 v[70:73], v[154:157], v[212:215], v[70:73]
	v_mfma_f32_16x16x32_bf16 v[66:69], v[162:165], v[212:215], v[66:69]
	s_setprio 0
	s_barrier
	s_add_i32 s8, s9, s14
	v_lshl_add_u64 v[186:187], s[2:3], 0, v[170:171]
	s_mov_b32 m0, s8
	ds_read_b128 v[166:169], v191 offset:16384
	ds_read_b128 v[182:185], v191 offset:17408
	ds_read_b128 v[192:195], v191 offset:18432
	ds_read_b128 v[196:199], v191 offset:19456
	ds_read_b128 v[200:203], v191 offset:20480
	ds_read_b128 v[204:207], v191 offset:21504
	ds_read_b128 v[208:211], v191 offset:22528
	ds_read_b128 v[212:215], v191 offset:23552
	global_load_lds_dwordx4 v[186:187], off
	s_add_i32 m0, s8, 0x2000
	s_add_u32 s8, s2, 0x40000
	v_lshl_add_u64 v[236:237], s[2:3], 0, v[172:173]
	s_addc_u32 s9, s3, 0
	s_add_i32 s7, s7, s14
	global_load_lds_dwordx4 v[236:237], off
	v_lshl_add_u64 v[238:239], s[8:9], 0, v[170:171]
	s_mov_b32 m0, s7
	v_lshl_add_u64 v[244:245], s[4:5], 0, v[176:177]
	global_load_lds_dwordx4 v[238:239], off
	v_lshl_add_u64 v[238:239], s[8:9], 0, v[172:173]
	s_add_i32 m0, s7, 0x2000
	s_nop 0
	global_load_lds_dwordx4 v[238:239], off
	v_lshl_add_u64 v[238:239], s[4:5], 0, v[174:175]
	s_mov_b32 m0, s15
	s_nop 0
	global_load_lds_dwordx4 v[238:239], off
	s_mov_b32 m0, s17
	s_nop 0
	global_load_lds_dwordx4 v[244:245], off
	s_waitcnt vmcnt(8)
	s_waitcnt lgkmcnt(0)
	s_barrier
	s_setprio 1
	v_mfma_f32_16x16x32_bf16 v[62:65], v[134:137], v[166:169], v[62:65]
	v_mfma_f32_16x16x32_bf16 v[58:61], v[142:145], v[166:169], v[58:61]
	v_mfma_f32_16x16x32_bf16 v[54:57], v[134:137], v[192:195], v[54:57]
	v_mfma_f32_16x16x32_bf16 v[50:53], v[142:145], v[192:195], v[50:53]
	v_mfma_f32_16x16x32_bf16 v[46:49], v[134:137], v[200:203], v[46:49]
	v_mfma_f32_16x16x32_bf16 v[42:45], v[142:145], v[200:203], v[42:45]
	v_mfma_f32_16x16x32_bf16 v[38:41], v[134:137], v[208:211], v[38:41]
	v_mfma_f32_16x16x32_bf16 v[34:37], v[142:145], v[208:211], v[34:37]
	v_mfma_f32_16x16x32_bf16 v[62:65], v[138:141], v[182:185], v[62:65]
	v_mfma_f32_16x16x32_bf16 v[58:61], v[146:149], v[182:185], v[58:61]
	v_mfma_f32_16x16x32_bf16 v[54:57], v[138:141], v[196:199], v[54:57]
	v_mfma_f32_16x16x32_bf16 v[50:53], v[146:149], v[196:199], v[50:53]
	v_mfma_f32_16x16x32_bf16 v[46:49], v[138:141], v[204:207], v[46:49]
	v_mfma_f32_16x16x32_bf16 v[42:45], v[146:149], v[204:207], v[42:45]
	v_mfma_f32_16x16x32_bf16 v[38:41], v[138:141], v[212:215], v[38:41]
	v_mfma_f32_16x16x32_bf16 v[34:37], v[146:149], v[212:215], v[34:37]
	v_mfma_f32_16x16x32_bf16 v[30:33], v[150:153], v[166:169], v[30:33]
	v_mfma_f32_16x16x32_bf16 v[26:29], v[158:161], v[166:169], v[26:29]
	v_mfma_f32_16x16x32_bf16 v[22:25], v[150:153], v[192:195], v[22:25]
	v_mfma_f32_16x16x32_bf16 v[18:21], v[158:161], v[192:195], v[18:21]
	v_mfma_f32_16x16x32_bf16 v[14:17], v[150:153], v[200:203], v[14:17]
	v_mfma_f32_16x16x32_bf16 v[10:13], v[158:161], v[200:203], v[10:13]
	v_mfma_f32_16x16x32_bf16 v[6:9], v[150:153], v[208:211], v[6:9]
	v_mfma_f32_16x16x32_bf16 v[2:5], v[158:161], v[208:211], v[2:5]
	v_mfma_f32_16x16x32_bf16 v[30:33], v[154:157], v[182:185], v[30:33]
	v_mfma_f32_16x16x32_bf16 v[26:29], v[162:165], v[182:185], v[26:29]
	v_mfma_f32_16x16x32_bf16 v[22:25], v[154:157], v[196:199], v[22:25]
	v_mfma_f32_16x16x32_bf16 v[18:21], v[162:165], v[196:199], v[18:21]
	v_mfma_f32_16x16x32_bf16 v[14:17], v[154:157], v[204:207], v[14:17]
	v_mfma_f32_16x16x32_bf16 v[10:13], v[162:165], v[204:207], v[10:13]
	v_mfma_f32_16x16x32_bf16 v[6:9], v[154:157], v[212:215], v[6:9]
	v_mfma_f32_16x16x32_bf16 v[2:5], v[162:165], v[212:215], v[2:5]
	s_setprio 0
	s_barrier
	s_add_i32 s7, 0, 0x18000
	v_add_u32_e32 v0, s7, v190
	s_add_i32 s8, 0, 0x1c000
	ds_read_b128 v[134:137], v0
	ds_read_b128 v[138:141], v0 offset:1024
	ds_read_b128 v[142:145], v0 offset:2048
	ds_read_b128 v[146:149], v0 offset:3072
	v_add_u32_e32 v0, s8, v190
	ds_read_b128 v[150:153], v0
	ds_read_b128 v[154:157], v0 offset:1024
	ds_read_b128 v[158:161], v0 offset:2048
	ds_read_b128 v[162:165], v0 offset:3072
	s_add_u32 s4, s4, 0x40000
	s_addc_u32 s5, s5, 0
	s_mov_b32 m0, s19
	v_lshl_add_u64 v[246:247], s[4:5], 0, v[174:175]
	ds_read_b128 v[166:169], v191 offset:32768
	ds_read_b128 v[182:185], v191 offset:33792
	ds_read_b128 v[192:195], v191 offset:34816
	ds_read_b128 v[196:199], v191 offset:35840
	ds_read_b128 v[200:203], v191 offset:36864
	ds_read_b128 v[204:207], v191 offset:37888
	ds_read_b128 v[208:211], v191 offset:38912
	ds_read_b128 v[212:215], v191 offset:39936
	global_load_lds_dwordx4 v[246:247], off
	v_lshl_add_u64 v[246:247], s[4:5], 0, v[176:177]
	s_mov_b32 m0, s40
	s_nop 0
	global_load_lds_dwordx4 v[246:247], off
	s_waitcnt vmcnt(8)
	s_waitcnt lgkmcnt(0)
	s_barrier
	s_setprio 1
	v_mfma_f32_16x16x32_bf16 v[126:129], v[134:137], v[166:169], v[126:129]
	v_mfma_f32_16x16x32_bf16 v[122:125], v[142:145], v[166:169], v[122:125]
	v_mfma_f32_16x16x32_bf16 v[118:121], v[134:137], v[192:195], v[118:121]
	v_mfma_f32_16x16x32_bf16 v[114:117], v[142:145], v[192:195], v[114:117]
	v_mfma_f32_16x16x32_bf16 v[110:113], v[134:137], v[200:203], v[110:113]
	v_mfma_f32_16x16x32_bf16 v[106:109], v[142:145], v[200:203], v[106:109]
	v_mfma_f32_16x16x32_bf16 v[102:105], v[134:137], v[208:211], v[102:105]
	v_mfma_f32_16x16x32_bf16 v[98:101], v[142:145], v[208:211], v[98:101]
	v_mfma_f32_16x16x32_bf16 v[126:129], v[138:141], v[182:185], v[126:129]
	v_mfma_f32_16x16x32_bf16 v[122:125], v[146:149], v[182:185], v[122:125]
	v_mfma_f32_16x16x32_bf16 v[118:121], v[138:141], v[196:199], v[118:121]
	v_mfma_f32_16x16x32_bf16 v[114:117], v[146:149], v[196:199], v[114:117]
	v_mfma_f32_16x16x32_bf16 v[110:113], v[138:141], v[204:207], v[110:113]
	v_mfma_f32_16x16x32_bf16 v[106:109], v[146:149], v[204:207], v[106:109]
	v_mfma_f32_16x16x32_bf16 v[102:105], v[138:141], v[212:215], v[102:105]
	v_mfma_f32_16x16x32_bf16 v[98:101], v[146:149], v[212:215], v[98:101]
	v_mfma_f32_16x16x32_bf16 v[94:97], v[150:153], v[166:169], v[94:97]
	v_mfma_f32_16x16x32_bf16 v[90:93], v[158:161], v[166:169], v[90:93]
	v_mfma_f32_16x16x32_bf16 v[86:89], v[150:153], v[192:195], v[86:89]
	v_mfma_f32_16x16x32_bf16 v[82:85], v[158:161], v[192:195], v[82:85]
	v_mfma_f32_16x16x32_bf16 v[78:81], v[150:153], v[200:203], v[78:81]
	v_mfma_f32_16x16x32_bf16 v[74:77], v[158:161], v[200:203], v[74:77]
	v_mfma_f32_16x16x32_bf16 v[70:73], v[150:153], v[208:211], v[70:73]
	v_mfma_f32_16x16x32_bf16 v[66:69], v[158:161], v[208:211], v[66:69]
	v_mfma_f32_16x16x32_bf16 v[94:97], v[154:157], v[182:185], v[94:97]
	v_mfma_f32_16x16x32_bf16 v[90:93], v[162:165], v[182:185], v[90:93]
	v_mfma_f32_16x16x32_bf16 v[86:89], v[154:157], v[196:199], v[86:89]
	v_mfma_f32_16x16x32_bf16 v[82:85], v[162:165], v[196:199], v[82:85]
	v_mfma_f32_16x16x32_bf16 v[78:81], v[154:157], v[204:207], v[78:81]
	v_mfma_f32_16x16x32_bf16 v[74:77], v[162:165], v[204:207], v[74:77]
	v_mfma_f32_16x16x32_bf16 v[70:73], v[154:157], v[212:215], v[70:73]
	v_mfma_f32_16x16x32_bf16 v[66:69], v[162:165], v[212:215], v[66:69]
	s_setprio 0
	s_barrier
	s_add_i32 s4, s7, s14
	v_lshl_add_u64 v[186:187], v[186:187], 0, s[42:43]
	s_mov_b32 m0, s4
	ds_read_b128 v[166:169], v191 offset:49152
	ds_read_b128 v[182:185], v191 offset:50176
	ds_read_b128 v[192:195], v191 offset:51200
	ds_read_b128 v[196:199], v191 offset:52224
	ds_read_b128 v[200:203], v191 offset:53248
	ds_read_b128 v[204:207], v191 offset:54272
	ds_read_b128 v[208:211], v191 offset:55296
	ds_read_b128 v[212:215], v191 offset:56320
	global_load_lds_dwordx4 v[186:187], off
	s_add_i32 m0, s4, 0x2000
	s_add_u32 s2, s2, 0x40080
	v_lshl_add_u64 v[186:187], v[236:237], 0, s[42:43]
	s_addc_u32 s3, s3, 0
	s_add_i32 s4, s8, s14
	global_load_lds_dwordx4 v[186:187], off
	v_lshl_add_u64 v[186:187], s[2:3], 0, v[170:171]
	s_mov_b32 m0, s4
	s_nop 0
	global_load_lds_dwordx4 v[186:187], off
	v_lshl_add_u64 v[186:187], s[2:3], 0, v[172:173]
	s_add_i32 m0, s4, 0x2000
	s_nop 0
	global_load_lds_dwordx4 v[186:187], off
	v_lshl_add_u64 v[186:187], v[238:239], 0, s[42:43]
	s_mov_b32 m0, s50
	s_nop 0
	global_load_lds_dwordx4 v[186:187], off
	v_lshl_add_u64 v[186:187], v[244:245], 0, s[42:43]
	s_mov_b32 m0, s51
	s_nop 0
	global_load_lds_dwordx4 v[186:187], off
	s_waitcnt vmcnt(8)
	s_waitcnt lgkmcnt(0)
	s_barrier
	s_setprio 1
	v_mfma_f32_16x16x32_bf16 v[62:65], v[134:137], v[166:169], v[62:65]
	v_mfma_f32_16x16x32_bf16 v[58:61], v[142:145], v[166:169], v[58:61]
	v_mfma_f32_16x16x32_bf16 v[54:57], v[134:137], v[192:195], v[54:57]
	v_mfma_f32_16x16x32_bf16 v[50:53], v[142:145], v[192:195], v[50:53]
	v_mfma_f32_16x16x32_bf16 v[46:49], v[134:137], v[200:203], v[46:49]
	v_mfma_f32_16x16x32_bf16 v[42:45], v[142:145], v[200:203], v[42:45]
	v_mfma_f32_16x16x32_bf16 v[38:41], v[134:137], v[208:211], v[38:41]
	v_mfma_f32_16x16x32_bf16 v[34:37], v[142:145], v[208:211], v[34:37]
	v_mfma_f32_16x16x32_bf16 v[62:65], v[138:141], v[182:185], v[62:65]
	v_mfma_f32_16x16x32_bf16 v[58:61], v[146:149], v[182:185], v[58:61]
	v_mfma_f32_16x16x32_bf16 v[54:57], v[138:141], v[196:199], v[54:57]
	v_mfma_f32_16x16x32_bf16 v[50:53], v[146:149], v[196:199], v[50:53]
	v_mfma_f32_16x16x32_bf16 v[46:49], v[138:141], v[204:207], v[46:49]
	v_mfma_f32_16x16x32_bf16 v[42:45], v[146:149], v[204:207], v[42:45]
	v_mfma_f32_16x16x32_bf16 v[38:41], v[138:141], v[212:215], v[38:41]
	v_mfma_f32_16x16x32_bf16 v[34:37], v[146:149], v[212:215], v[34:37]
	v_mfma_f32_16x16x32_bf16 v[30:33], v[150:153], v[166:169], v[30:33]
	v_mfma_f32_16x16x32_bf16 v[26:29], v[158:161], v[166:169], v[26:29]
	v_mfma_f32_16x16x32_bf16 v[22:25], v[150:153], v[192:195], v[22:25]
	v_mfma_f32_16x16x32_bf16 v[18:21], v[158:161], v[192:195], v[18:21]
	v_mfma_f32_16x16x32_bf16 v[14:17], v[150:153], v[200:203], v[14:17]
	v_mfma_f32_16x16x32_bf16 v[10:13], v[158:161], v[200:203], v[10:13]
	v_mfma_f32_16x16x32_bf16 v[6:9], v[150:153], v[208:211], v[6:9]
	v_mfma_f32_16x16x32_bf16 v[2:5], v[158:161], v[208:211], v[2:5]
	v_mfma_f32_16x16x32_bf16 v[30:33], v[154:157], v[182:185], v[30:33]
	v_mfma_f32_16x16x32_bf16 v[26:29], v[162:165], v[182:185], v[26:29]
	v_mfma_f32_16x16x32_bf16 v[22:25], v[154:157], v[196:199], v[22:25]
	v_mfma_f32_16x16x32_bf16 v[18:21], v[162:165], v[196:199], v[18:21]
	v_mfma_f32_16x16x32_bf16 v[14:17], v[154:157], v[204:207], v[14:17]
	v_mfma_f32_16x16x32_bf16 v[10:13], v[162:165], v[204:207], v[10:13]
	v_mfma_f32_16x16x32_bf16 v[6:9], v[154:157], v[212:215], v[6:9]
	v_mfma_f32_16x16x32_bf16 v[2:5], v[162:165], v[212:215], v[2:5]
	s_setprio 0
	s_barrier
	s_add_i32 s6, s6, 2
	s_add_u32 s0, s0, 0x100
	s_addc_u32 s1, s1, 0
	s_cmp_gt_u32 s6, 13
	s_cbranch_scc0 .LBB0_315
.Lkp_exit_up:
	s_and_b64 vcc, exec, s[36:37]
	s_cbranch_vccz .LBB0_318
	s_barrier

.LBB0_1010:
	s_mov_b64 s[8:9], 0x80
	v_lshl_add_u64 v[2:3], v[2:3], 0, s[8:9]
	s_add_i32 m0, s49, 0x18000
	s_waitcnt vmcnt(2)
	s_barrier
	global_load_lds_dwordx4 v[2:3], off
	v_lshl_add_u64 v[2:3], v[4:5], 0, s[8:9]
	s_add_i32 m0, s49, 0x1a000
	s_add_i32 s56, s49, 0x8000
	global_load_lds_dwordx4 v[2:3], off
	v_lshl_add_u64 v[2:3], v[10:11], 0, s[8:9]
	s_mov_b32 m0, s56
	s_add_i32 s57, s49, 0xa000
	global_load_lds_dwordx4 v[2:3], off
	v_lshl_add_u64 v[2:3], v[12:13], 0, s[8:9]
	s_mov_b32 m0, s57
	v_bfe_u32 v179, v14, 4, 2
	global_load_lds_dwordx4 v[2:3], off
	v_lshl_add_u64 v[2:3], v[6:7], 0, s[8:9]
	s_add_i32 m0, s49, 0x1c000
	v_and_b32_e32 v178, 15, v14
	global_load_lds_dwordx4 v[2:3], off
	v_lshl_add_u64 v[2:3], v[8:9], 0, s[8:9]
	s_add_i32 m0, s49, 0x1e000
	v_lshlrev_b32_e32 v0, 4, v179
	global_load_lds_dwordx4 v[2:3], off
	v_lshlrev_b32_e32 v14, 2, v14
	s_and_b32 s4, s3, 3
	v_lshl_or_b32 v0, v178, 6, v0
	s_lshl_b32 s5, s2, 13
	v_and_b32_e32 v14, 32, v14
	s_lshl_b32 s54, s2, 6
	v_bitop3_b32 v18, v0, s5, v14 bitop3:0xde
	s_lshl_b32 s55, s4, 5
	s_lshl_b32 s5, s4, 12
	s_cmpk_lt_u32 s6, 0x100
	s_cselect_b64 s[18:19], -1, 0
	s_add_u32 s20, s82, 0x4e00000
	v_bitop3_b32 v180, v0, s5, v14 bitop3:0xde
	s_addc_u32 s21, s83, 0
	s_bfe_u32 s5, s6, 0x10006
	s_cmp_eq_u32 s5, 0
	s_cselect_b64 s[22:23], -1, 0
	s_lshl_b32 s2, s2, 2
	s_or_b32 s2, s2, s4
	s_bfe_u32 s58, s3, 0x10001
	s_ashr_i32 s3, s2, 31
	s_lshl_b32 s59, s5, 5
	s_lshl_b32 s60, s75, 14
	s_lshl_b64 s[24:25], s[2:3], 10
	s_add_u32 s26, s82, 0xd800000
	s_mul_i32 s2, s7, 0x2600000
	s_addc_u32 s27, s83, 0
	s_ashr_i32 s3, s2, 31
	s_add_u32 s61, s82, 0x15000000
	s_addc_u32 s62, s83, 0
	s_lshr_b32 s63, s12, 3
	s_add_u32 s2, s82, s2
	s_addc_u32 s3, s83, s3
	s_add_u32 s64, s2, 0x100000
	s_addc_u32 s65, s3, 0
	s_add_u32 s28, s82, 0xf000000
	s_addc_u32 s29, s83, 0
	s_add_u32 s30, s82, 0x7800000
	v_lshlrev_b32_e32 v0, 14, v15
	s_addc_u32 s31, s83, 0
	v_and_b32_e32 v0, 0xffff8000, v0
	s_add_u32 s44, s82, 0x5400000
	v_and_b32_e32 v2, 1, v15
	v_lshl_add_u32 v0, v16, 11, v0
	s_waitcnt vmcnt(6)
	v_readlane_b32 s4, v252, 39
	s_addc_u32 s66, s83, 0
	v_lshl_or_b32 v0, v2, 6, v0
	v_readlane_b32 s5, v252, 40
	s_add_u32 s67, s82, 0x5000000
	v_lshl_add_u32 v144, v17, 1, v0
	s_mov_b32 s40, 0
	s_mov_b32 s13, s5
	s_addc_u32 s68, s83, 0
	v_add_u32_e32 v146, 0x20000, v144
	v_mov_b32_e32 v147, v1
	v_mov_b32_e32 v145, v1
	v_add_u32_e32 v181, 0, v18
	s_mov_b64 s[38:39], s[0:1]
	s_barrier
	s_branch .LBB0_1012
.LBB0_1011:
	s_mov_b32 s50, s73
	s_mov_b64 s[14:15], s[46:47]
	s_mov_b32 s40, s72
	s_andn2_b64 vcc, exec, s[8:9]
	s_mov_b64 s[0:1], s[38:39]
	s_cbranch_vccz .LBB0_1126

.LBB0_1025:
	s_add_u32 s74, s0, 0x100
	s_addc_u32 s75, s1, 0
	s_add_u32 s0, s14, 0x40080
	s_addc_u32 s1, s15, 0
	v_lshl_add_u64 v[130:131], s[0:1], 0, v[146:147]
	v_lshl_add_u64 v[132:133], s[0:1], 0, v[144:145]
	s_mov_b32 s6, -2
	s_mov_b64 s[0:1], 0
	s_mov_b64 s[42:43], 0x80
	s_add_u32 s2, s14, s0
	s_addc_u32 s3, s15, s1
	s_add_u32 s2, s2, 0x100
	s_addc_u32 s3, s3, 0
	s_add_u32 s7, s74, s0
	s_addc_u32 s37, s75, s1
	s_add_i32 s80, 0, 0x10000
	s_add_i32 s81, 0, 0x14000
	v_add_u32_e32 v0, s80, v180
	ds_read_b128 v[134:137], v0
	ds_read_b128 v[148:151], v0 offset:1024
	ds_read_b128 v[152:155], v0 offset:2048
	ds_read_b128 v[156:159], v0 offset:3072
	v_add_u32_e32 v0, s81, v180
	ds_read_b128 v[160:163], v0
	ds_read_b128 v[164:167], v0 offset:1024
	ds_read_b128 v[168:171], v0 offset:2048
	ds_read_b128 v[172:175], v0 offset:3072
	s_cmpk_eq_i32 s0, 0x700
	s_cselect_b32 s3, s47, s3
	s_cselect_b32 s2, s46, s2
	s_cselect_b32 s77, s39, s37
	s_cselect_b32 s76, s38, s7
	s_cselect_b32 s7, s73, s50
	v_lshl_add_u64 v[176:177], v[132:133], 0, s[0:1]
	s_add_i32 m0, s49, 0xc000
	ds_read_b128 v[182:185], v181
	ds_read_b128 v[186:189], v181 offset:1024
	ds_read_b128 v[190:193], v181 offset:2048
	ds_read_b128 v[194:197], v181 offset:3072
	ds_read_b128 v[198:201], v181 offset:4096
	ds_read_b128 v[202:205], v181 offset:5120
	ds_read_b128 v[206:209], v181 offset:6144
	ds_read_b128 v[210:213], v181 offset:7168
	global_load_lds_dwordx4 v[176:177], off
	v_lshl_add_u64 v[176:177], v[130:131], 0, s[0:1]
	s_add_i32 m0, s49, 0xe000
	s_nop 0
	global_load_lds_dwordx4 v[176:177], off
	s_waitcnt vmcnt(8)
	s_waitcnt lgkmcnt(0)
	s_barrier
	s_setprio 1
	v_mfma_f32_16x16x32_bf16 v[126:129], v[134:137], v[182:185], 0
	v_mfma_f32_16x16x32_bf16 v[122:125], v[152:155], v[182:185], 0
	v_mfma_f32_16x16x32_bf16 v[118:121], v[134:137], v[190:193], 0
	v_mfma_f32_16x16x32_bf16 v[114:117], v[152:155], v[190:193], 0
	v_mfma_f32_16x16x32_bf16 v[110:113], v[134:137], v[198:201], 0
	v_mfma_f32_16x16x32_bf16 v[106:109], v[152:155], v[198:201], 0
	v_mfma_f32_16x16x32_bf16 v[102:105], v[134:137], v[206:209], 0
	v_mfma_f32_16x16x32_bf16 v[98:101], v[152:155], v[206:209], 0
	v_mfma_f32_16x16x32_bf16 v[126:129], v[148:151], v[186:189], v[126:129]
	v_mfma_f32_16x16x32_bf16 v[122:125], v[156:159], v[186:189], v[122:125]
	v_mfma_f32_16x16x32_bf16 v[118:121], v[148:151], v[194:197], v[118:121]
	v_mfma_f32_16x16x32_bf16 v[114:117], v[156:159], v[194:197], v[114:117]
	v_mfma_f32_16x16x32_bf16 v[110:113], v[148:151], v[202:205], v[110:113]
	v_mfma_f32_16x16x32_bf16 v[106:109], v[156:159], v[202:205], v[106:109]
	v_mfma_f32_16x16x32_bf16 v[102:105], v[148:151], v[210:213], v[102:105]
	v_mfma_f32_16x16x32_bf16 v[98:101], v[156:159], v[210:213], v[98:101]
	v_mfma_f32_16x16x32_bf16 v[94:97], v[160:163], v[182:185], 0
	v_mfma_f32_16x16x32_bf16 v[90:93], v[168:171], v[182:185], 0
	v_mfma_f32_16x16x32_bf16 v[86:89], v[160:163], v[190:193], 0
	v_mfma_f32_16x16x32_bf16 v[82:85], v[168:171], v[190:193], 0
	v_mfma_f32_16x16x32_bf16 v[78:81], v[160:163], v[198:201], 0
	v_mfma_f32_16x16x32_bf16 v[74:77], v[168:171], v[198:201], 0
	v_mfma_f32_16x16x32_bf16 v[70:73], v[160:163], v[206:209], 0
	v_mfma_f32_16x16x32_bf16 v[66:69], v[168:171], v[206:209], 0
	v_mfma_f32_16x16x32_bf16 v[94:97], v[164:167], v[186:189], v[94:97]
	v_mfma_f32_16x16x32_bf16 v[90:93], v[172:175], v[186:189], v[90:93]
	v_mfma_f32_16x16x32_bf16 v[86:89], v[164:167], v[194:197], v[86:89]
	v_mfma_f32_16x16x32_bf16 v[82:85], v[172:175], v[194:197], v[82:85]
	v_mfma_f32_16x16x32_bf16 v[78:81], v[164:167], v[202:205], v[78:81]
	v_mfma_f32_16x16x32_bf16 v[74:77], v[172:175], v[202:205], v[74:77]
	v_mfma_f32_16x16x32_bf16 v[70:73], v[164:167], v[210:213], v[70:73]
	v_mfma_f32_16x16x32_bf16 v[66:69], v[172:175], v[210:213], v[66:69]
	s_setprio 0
	s_barrier
	s_add_i32 s37, s80, s48
	v_mad_u64_u32 v[176:177], s[78:79], s7, v139, v[138:139]
	s_mov_b32 m0, s37
	ds_read_b128 v[182:185], v181 offset:16384
	ds_read_b128 v[186:189], v181 offset:17408
	ds_read_b128 v[190:193], v181 offset:18432
	ds_read_b128 v[194:197], v181 offset:19456
	ds_read_b128 v[198:201], v181 offset:20480
	ds_read_b128 v[202:205], v181 offset:21504
	ds_read_b128 v[206:209], v181 offset:22528
	ds_read_b128 v[210:213], v181 offset:23552
	v_mov_b32_e32 v177, v1
	global_load_lds_dwordx4 v176, s[76:77]
	v_lshl_add_u32 v0, s7, 6, v176
	s_add_i32 m0, s37, 0x2000
	s_lshl_b32 s7, s7, 7
	v_lshl_add_u64 v[214:215], s[76:77], 0, v[176:177]
	v_lshl_add_u64 v[236:237], s[76:77], 0, v[0:1]
	global_load_lds_dwordx4 v0, s[76:77]
	s_add_u32 s76, s76, s7
	s_addc_u32 s77, s77, 0
	s_add_i32 s7, s81, s48
	s_mov_b32 m0, s7
	v_lshl_add_u64 v[246:247], s[2:3], 0, v[140:141]
	global_load_lds_dwordx4 v176, s[76:77]
	s_add_i32 m0, s7, 0x2000
	v_lshl_add_u64 v[248:249], s[2:3], 0, v[142:143]
	global_load_lds_dwordx4 v0, s[76:77]
	s_mov_b32 m0, s49
	v_lshl_add_u64 v[238:239], s[76:77], 0, v[176:177]
	global_load_lds_dwordx4 v[246:247], off
	s_mov_b32 m0, s51
	v_lshl_add_u64 v[176:177], s[76:77], 0, v[0:1]
	global_load_lds_dwordx4 v[248:249], off
	s_waitcnt vmcnt(8)
	s_waitcnt lgkmcnt(0)
	s_barrier
	s_setprio 1
	v_mfma_f32_16x16x32_bf16 v[62:65], v[134:137], v[182:185], 0
	v_mfma_f32_16x16x32_bf16 v[58:61], v[152:155], v[182:185], 0
	v_mfma_f32_16x16x32_bf16 v[54:57], v[134:137], v[190:193], 0
	v_mfma_f32_16x16x32_bf16 v[50:53], v[152:155], v[190:193], 0
	v_mfma_f32_16x16x32_bf16 v[46:49], v[134:137], v[198:201], 0
	v_mfma_f32_16x16x32_bf16 v[42:45], v[152:155], v[198:201], 0
	v_mfma_f32_16x16x32_bf16 v[38:41], v[134:137], v[206:209], 0
	v_mfma_f32_16x16x32_bf16 v[34:37], v[152:155], v[206:209], 0
	v_mfma_f32_16x16x32_bf16 v[62:65], v[148:151], v[186:189], v[62:65]
	v_mfma_f32_16x16x32_bf16 v[58:61], v[156:159], v[186:189], v[58:61]
	v_mfma_f32_16x16x32_bf16 v[54:57], v[148:151], v[194:197], v[54:57]
	v_mfma_f32_16x16x32_bf16 v[50:53], v[156:159], v[194:197], v[50:53]
	v_mfma_f32_16x16x32_bf16 v[46:49], v[148:151], v[202:205], v[46:49]
	v_mfma_f32_16x16x32_bf16 v[42:45], v[156:159], v[202:205], v[42:45]
	v_mfma_f32_16x16x32_bf16 v[38:41], v[148:151], v[210:213], v[38:41]
	v_mfma_f32_16x16x32_bf16 v[34:37], v[156:159], v[210:213], v[34:37]
	v_mfma_f32_16x16x32_bf16 v[30:33], v[160:163], v[182:185], 0
	v_mfma_f32_16x16x32_bf16 v[26:29], v[168:171], v[182:185], 0
	v_mfma_f32_16x16x32_bf16 v[22:25], v[160:163], v[190:193], 0
	v_mfma_f32_16x16x32_bf16 v[18:21], v[168:171], v[190:193], 0
	v_mfma_f32_16x16x32_bf16 v[14:17], v[160:163], v[198:201], 0
	v_mfma_f32_16x16x32_bf16 v[10:13], v[168:171], v[198:201], 0
	v_mfma_f32_16x16x32_bf16 v[6:9], v[160:163], v[206:209], 0
	v_mfma_f32_16x16x32_bf16 v[2:5], v[168:171], v[206:209], 0
	v_mfma_f32_16x16x32_bf16 v[30:33], v[164:167], v[186:189], v[30:33]
	v_mfma_f32_16x16x32_bf16 v[26:29], v[172:175], v[186:189], v[26:29]
	v_mfma_f32_16x16x32_bf16 v[22:25], v[164:167], v[194:197], v[22:25]
	v_mfma_f32_16x16x32_bf16 v[18:21], v[172:175], v[194:197], v[18:21]
	v_mfma_f32_16x16x32_bf16 v[14:17], v[164:167], v[202:205], v[14:17]
	v_mfma_f32_16x16x32_bf16 v[10:13], v[172:175], v[202:205], v[10:13]
	v_mfma_f32_16x16x32_bf16 v[6:9], v[164:167], v[210:213], v[6:9]
	v_mfma_f32_16x16x32_bf16 v[2:5], v[172:175], v[210:213], v[2:5]
	s_setprio 0
	s_barrier
	s_add_i32 s7, 0, 0x18000
	v_add_u32_e32 v0, s7, v180
	s_add_i32 s37, 0, 0x1c000
	ds_read_b128 v[134:137], v0
	ds_read_b128 v[148:151], v0 offset:1024
	ds_read_b128 v[152:155], v0 offset:2048
	ds_read_b128 v[156:159], v0 offset:3072
	v_add_u32_e32 v0, s37, v180
	ds_read_b128 v[160:163], v0
	ds_read_b128 v[164:167], v0 offset:1024
	ds_read_b128 v[168:171], v0 offset:2048
	ds_read_b128 v[172:175], v0 offset:3072
	s_add_u32 s2, s2, 0x40000
	s_addc_u32 s3, s3, 0
	s_mov_b32 m0, s52
	v_lshl_add_u64 v[244:245], s[2:3], 0, v[140:141]
	ds_read_b128 v[182:185], v181 offset:32768
	ds_read_b128 v[186:189], v181 offset:33792
	ds_read_b128 v[190:193], v181 offset:34816
	ds_read_b128 v[194:197], v181 offset:35840
	ds_read_b128 v[198:201], v181 offset:36864
	ds_read_b128 v[202:205], v181 offset:37888
	ds_read_b128 v[206:209], v181 offset:38912
	ds_read_b128 v[210:213], v181 offset:39936
	global_load_lds_dwordx4 v[244:245], off
	v_lshl_add_u64 v[244:245], s[2:3], 0, v[142:143]
	s_mov_b32 m0, s53
	s_nop 0
	global_load_lds_dwordx4 v[244:245], off
	s_waitcnt vmcnt(8)
	s_waitcnt lgkmcnt(0)
	s_barrier
	s_setprio 1
	v_mfma_f32_16x16x32_bf16 v[126:129], v[134:137], v[182:185], v[126:129]
	v_mfma_f32_16x16x32_bf16 v[122:125], v[152:155], v[182:185], v[122:125]
	v_mfma_f32_16x16x32_bf16 v[118:121], v[134:137], v[190:193], v[118:121]
	v_mfma_f32_16x16x32_bf16 v[114:117], v[152:155], v[190:193], v[114:117]
	v_mfma_f32_16x16x32_bf16 v[110:113], v[134:137], v[198:201], v[110:113]
	v_mfma_f32_16x16x32_bf16 v[106:109], v[152:155], v[198:201], v[106:109]
	v_mfma_f32_16x16x32_bf16 v[102:105], v[134:137], v[206:209], v[102:105]
	v_mfma_f32_16x16x32_bf16 v[98:101], v[152:155], v[206:209], v[98:101]
	v_mfma_f32_16x16x32_bf16 v[126:129], v[148:151], v[186:189], v[126:129]
	v_mfma_f32_16x16x32_bf16 v[122:125], v[156:159], v[186:189], v[122:125]
	v_mfma_f32_16x16x32_bf16 v[118:121], v[148:151], v[194:197], v[118:121]
	v_mfma_f32_16x16x32_bf16 v[114:117], v[156:159], v[194:197], v[114:117]
	v_mfma_f32_16x16x32_bf16 v[110:113], v[148:151], v[202:205], v[110:113]
	v_mfma_f32_16x16x32_bf16 v[106:109], v[156:159], v[202:205], v[106:109]
	v_mfma_f32_16x16x32_bf16 v[102:105], v[148:151], v[210:213], v[102:105]
	v_mfma_f32_16x16x32_bf16 v[98:101], v[156:159], v[210:213], v[98:101]
	v_mfma_f32_16x16x32_bf16 v[94:97], v[160:163], v[182:185], v[94:97]
	v_mfma_f32_16x16x32_bf16 v[90:93], v[168:171], v[182:185], v[90:93]
	v_mfma_f32_16x16x32_bf16 v[86:89], v[160:163], v[190:193], v[86:89]
	v_mfma_f32_16x16x32_bf16 v[82:85], v[168:171], v[190:193], v[82:85]
	v_mfma_f32_16x16x32_bf16 v[78:81], v[160:163], v[198:201], v[78:81]
	v_mfma_f32_16x16x32_bf16 v[74:77], v[168:171], v[198:201], v[74:77]
	v_mfma_f32_16x16x32_bf16 v[70:73], v[160:163], v[206:209], v[70:73]
	v_mfma_f32_16x16x32_bf16 v[66:69], v[168:171], v[206:209], v[66:69]
	v_mfma_f32_16x16x32_bf16 v[94:97], v[164:167], v[186:189], v[94:97]
	v_mfma_f32_16x16x32_bf16 v[90:93], v[172:175], v[186:189], v[90:93]
	v_mfma_f32_16x16x32_bf16 v[86:89], v[164:167], v[194:197], v[86:89]
	v_mfma_f32_16x16x32_bf16 v[82:85], v[172:175], v[194:197], v[82:85]
	v_mfma_f32_16x16x32_bf16 v[78:81], v[164:167], v[202:205], v[78:81]
	v_mfma_f32_16x16x32_bf16 v[74:77], v[172:175], v[202:205], v[74:77]
	v_mfma_f32_16x16x32_bf16 v[70:73], v[164:167], v[210:213], v[70:73]
	v_mfma_f32_16x16x32_bf16 v[66:69], v[172:175], v[210:213], v[66:69]
	s_setprio 0
	s_barrier
	s_add_i32 s2, s7, s48
	v_lshl_add_u64 v[214:215], v[214:215], 0, s[42:43]
	s_mov_b32 m0, s2
	ds_read_b128 v[182:185], v181 offset:49152
	ds_read_b128 v[186:189], v181 offset:50176
	ds_read_b128 v[190:193], v181 offset:51200
	ds_read_b128 v[194:197], v181 offset:52224
	ds_read_b128 v[198:201], v181 offset:53248
	ds_read_b128 v[202:205], v181 offset:54272
	ds_read_b128 v[206:209], v181 offset:55296
	ds_read_b128 v[210:213], v181 offset:56320
	global_load_lds_dwordx4 v[214:215], off
	v_lshl_add_u64 v[214:215], v[236:237], 0, s[42:43]
	s_add_i32 m0, s2, 0x2000
	s_add_i32 s2, s37, s48
	global_load_lds_dwordx4 v[214:215], off
	v_lshl_add_u64 v[214:215], v[238:239], 0, s[42:43]
	s_mov_b32 m0, s2
	v_lshl_add_u64 v[176:177], v[176:177], 0, s[42:43]
	global_load_lds_dwordx4 v[214:215], off
	s_add_i32 m0, s2, 0x2000
	s_nop 0
	global_load_lds_dwordx4 v[176:177], off
	v_lshl_add_u64 v[176:177], v[246:247], 0, s[42:43]
	s_mov_b32 m0, s56
	s_nop 0
	global_load_lds_dwordx4 v[176:177], off
	v_lshl_add_u64 v[176:177], v[248:249], 0, s[42:43]
	s_mov_b32 m0, s57
	s_nop 0
	global_load_lds_dwordx4 v[176:177], off
	s_waitcnt vmcnt(8)
	s_waitcnt lgkmcnt(0)
	s_barrier
	s_setprio 1
	v_mfma_f32_16x16x32_bf16 v[62:65], v[134:137], v[182:185], v[62:65]
	v_mfma_f32_16x16x32_bf16 v[58:61], v[152:155], v[182:185], v[58:61]
	v_mfma_f32_16x16x32_bf16 v[54:57], v[134:137], v[190:193], v[54:57]
	v_mfma_f32_16x16x32_bf16 v[50:53], v[152:155], v[190:193], v[50:53]
	v_mfma_f32_16x16x32_bf16 v[46:49], v[134:137], v[198:201], v[46:49]
	v_mfma_f32_16x16x32_bf16 v[42:45], v[152:155], v[198:201], v[42:45]
	v_mfma_f32_16x16x32_bf16 v[38:41], v[134:137], v[206:209], v[38:41]
	v_mfma_f32_16x16x32_bf16 v[34:37], v[152:155], v[206:209], v[34:37]
	v_mfma_f32_16x16x32_bf16 v[62:65], v[148:151], v[186:189], v[62:65]
	v_mfma_f32_16x16x32_bf16 v[58:61], v[156:159], v[186:189], v[58:61]
	v_mfma_f32_16x16x32_bf16 v[54:57], v[148:151], v[194:197], v[54:57]
	v_mfma_f32_16x16x32_bf16 v[50:53], v[156:159], v[194:197], v[50:53]
	v_mfma_f32_16x16x32_bf16 v[46:49], v[148:151], v[202:205], v[46:49]
	v_mfma_f32_16x16x32_bf16 v[42:45], v[156:159], v[202:205], v[42:45]
	v_mfma_f32_16x16x32_bf16 v[38:41], v[148:151], v[210:213], v[38:41]
	v_mfma_f32_16x16x32_bf16 v[34:37], v[156:159], v[210:213], v[34:37]
	v_mfma_f32_16x16x32_bf16 v[30:33], v[160:163], v[182:185], v[30:33]
	v_mfma_f32_16x16x32_bf16 v[26:29], v[168:171], v[182:185], v[26:29]
	v_mfma_f32_16x16x32_bf16 v[22:25], v[160:163], v[190:193], v[22:25]
	v_mfma_f32_16x16x32_bf16 v[18:21], v[168:171], v[190:193], v[18:21]
	v_mfma_f32_16x16x32_bf16 v[14:17], v[160:163], v[198:201], v[14:17]
	v_mfma_f32_16x16x32_bf16 v[10:13], v[168:171], v[198:201], v[10:13]
	v_mfma_f32_16x16x32_bf16 v[6:9], v[160:163], v[206:209], v[6:9]
	v_mfma_f32_16x16x32_bf16 v[2:5], v[168:171], v[206:209], v[2:5]
	v_mfma_f32_16x16x32_bf16 v[30:33], v[164:167], v[186:189], v[30:33]
	v_mfma_f32_16x16x32_bf16 v[26:29], v[172:175], v[186:189], v[26:29]
	v_mfma_f32_16x16x32_bf16 v[22:25], v[164:167], v[194:197], v[22:25]
	v_mfma_f32_16x16x32_bf16 v[18:21], v[172:175], v[194:197], v[18:21]
	v_mfma_f32_16x16x32_bf16 v[14:17], v[164:167], v[202:205], v[14:17]
	v_mfma_f32_16x16x32_bf16 v[10:13], v[172:175], v[202:205], v[10:13]
	v_mfma_f32_16x16x32_bf16 v[6:9], v[164:167], v[210:213], v[6:9]
	v_mfma_f32_16x16x32_bf16 v[2:5], v[172:175], v[210:213], v[2:5]
	s_setprio 0
	s_barrier
	s_add_i32 s6, s6, 2
	s_add_u32 s0, s0, 0x100
	s_addc_u32 s1, s1, 0
	s_cmp_gt_u32 s6, 13
	s_cbranch_scc1 .Lkp_exit_win
.LBB0_1026:
	s_add_u32 s2, s14, s0
	s_addc_u32 s3, s15, s1
	s_add_u32 s2, s2, 0x100
	s_addc_u32 s3, s3, 0
	s_add_u32 s7, s74, s0
	s_addc_u32 s37, s75, s1
	s_add_i32 s80, 0, 0x10000
	s_add_i32 s81, 0, 0x14000
	v_add_u32_e32 v0, s80, v180
	ds_read_b128 v[134:137], v0
	ds_read_b128 v[148:151], v0 offset:1024
	ds_read_b128 v[152:155], v0 offset:2048
	ds_read_b128 v[156:159], v0 offset:3072
	v_add_u32_e32 v0, s81, v180
	ds_read_b128 v[160:163], v0
	ds_read_b128 v[164:167], v0 offset:1024
	ds_read_b128 v[168:171], v0 offset:2048
	ds_read_b128 v[172:175], v0 offset:3072
	s_cmpk_eq_i32 s0, 0x700
	s_cselect_b32 s3, s47, s3
	s_cselect_b32 s2, s46, s2
	s_cselect_b32 s77, s39, s37
	s_cselect_b32 s76, s38, s7
	s_cselect_b32 s7, s73, s50
	v_lshl_add_u64 v[176:177], v[132:133], 0, s[0:1]
	s_add_i32 m0, s49, 0xc000
	ds_read_b128 v[182:185], v181
	ds_read_b128 v[186:189], v181 offset:1024
	ds_read_b128 v[190:193], v181 offset:2048
	ds_read_b128 v[194:197], v181 offset:3072
	ds_read_b128 v[198:201], v181 offset:4096
	ds_read_b128 v[202:205], v181 offset:5120
	ds_read_b128 v[206:209], v181 offset:6144
	ds_read_b128 v[210:213], v181 offset:7168
	global_load_lds_dwordx4 v[176:177], off
	v_lshl_add_u64 v[176:177], v[130:131], 0, s[0:1]
	s_add_i32 m0, s49, 0xe000
	s_nop 0
	global_load_lds_dwordx4 v[176:177], off
	s_waitcnt vmcnt(8)
	s_waitcnt lgkmcnt(0)
	s_barrier
	s_setprio 1
	v_mfma_f32_16x16x32_bf16 v[126:129], v[134:137], v[182:185], v[126:129]
	v_mfma_f32_16x16x32_bf16 v[122:125], v[152:155], v[182:185], v[122:125]
	v_mfma_f32_16x16x32_bf16 v[118:121], v[134:137], v[190:193], v[118:121]
	v_mfma_f32_16x16x32_bf16 v[114:117], v[152:155], v[190:193], v[114:117]
	v_mfma_f32_16x16x32_bf16 v[110:113], v[134:137], v[198:201], v[110:113]
	v_mfma_f32_16x16x32_bf16 v[106:109], v[152:155], v[198:201], v[106:109]
	v_mfma_f32_16x16x32_bf16 v[102:105], v[134:137], v[206:209], v[102:105]
	v_mfma_f32_16x16x32_bf16 v[98:101], v[152:155], v[206:209], v[98:101]
	v_mfma_f32_16x16x32_bf16 v[126:129], v[148:151], v[186:189], v[126:129]
	v_mfma_f32_16x16x32_bf16 v[122:125], v[156:159], v[186:189], v[122:125]
	v_mfma_f32_16x16x32_bf16 v[118:121], v[148:151], v[194:197], v[118:121]
	v_mfma_f32_16x16x32_bf16 v[114:117], v[156:159], v[194:197], v[114:117]
	v_mfma_f32_16x16x32_bf16 v[110:113], v[148:151], v[202:205], v[110:113]
	v_mfma_f32_16x16x32_bf16 v[106:109], v[156:159], v[202:205], v[106:109]
	v_mfma_f32_16x16x32_bf16 v[102:105], v[148:151], v[210:213], v[102:105]
	v_mfma_f32_16x16x32_bf16 v[98:101], v[156:159], v[210:213], v[98:101]
	v_mfma_f32_16x16x32_bf16 v[94:97], v[160:163], v[182:185], v[94:97]
	v_mfma_f32_16x16x32_bf16 v[90:93], v[168:171], v[182:185], v[90:93]
	v_mfma_f32_16x16x32_bf16 v[86:89], v[160:163], v[190:193], v[86:89]
	v_mfma_f32_16x16x32_bf16 v[82:85], v[168:171], v[190:193], v[82:85]
	v_mfma_f32_16x16x32_bf16 v[78:81], v[160:163], v[198:201], v[78:81]
	v_mfma_f32_16x16x32_bf16 v[74:77], v[168:171], v[198:201], v[74:77]
	v_mfma_f32_16x16x32_bf16 v[70:73], v[160:163], v[206:209], v[70:73]
	v_mfma_f32_16x16x32_bf16 v[66:69], v[168:171], v[206:209], v[66:69]
	v_mfma_f32_16x16x32_bf16 v[94:97], v[164:167], v[186:189], v[94:97]
	v_mfma_f32_16x16x32_bf16 v[90:93], v[172:175], v[186:189], v[90:93]
	v_mfma_f32_16x16x32_bf16 v[86:89], v[164:167], v[194:197], v[86:89]
	v_mfma_f32_16x16x32_bf16 v[82:85], v[172:175], v[194:197], v[82:85]
	v_mfma_f32_16x16x32_bf16 v[78:81], v[164:167], v[202:205], v[78:81]
	v_mfma_f32_16x16x32_bf16 v[74:77], v[172:175], v[202:205], v[74:77]
	v_mfma_f32_16x16x32_bf16 v[70:73], v[164:167], v[210:213], v[70:73]
	v_mfma_f32_16x16x32_bf16 v[66:69], v[172:175], v[210:213], v[66:69]
	s_setprio 0
	s_barrier
	s_add_i32 s37, s80, s48
	v_mad_u64_u32 v[176:177], s[78:79], s7, v139, v[138:139]
	s_mov_b32 m0, s37
	ds_read_b128 v[182:185], v181 offset:16384
	ds_read_b128 v[186:189], v181 offset:17408
	ds_read_b128 v[190:193], v181 offset:18432
	ds_read_b128 v[194:197], v181 offset:19456
	ds_read_b128 v[198:201], v181 offset:20480
	ds_read_b128 v[202:205], v181 offset:21504
	ds_read_b128 v[206:209], v181 offset:22528
	ds_read_b128 v[210:213], v181 offset:23552
	v_mov_b32_e32 v177, v1
	global_load_lds_dwordx4 v176, s[76:77]
	v_lshl_add_u32 v0, s7, 6, v176
	s_add_i32 m0, s37, 0x2000
	s_lshl_b32 s7, s7, 7
	v_lshl_add_u64 v[214:215], s[76:77], 0, v[176:177]
	v_lshl_add_u64 v[236:237], s[76:77], 0, v[0:1]
	global_load_lds_dwordx4 v0, s[76:77]
	s_add_u32 s76, s76, s7
	s_addc_u32 s77, s77, 0
	s_add_i32 s7, s81, s48
	s_mov_b32 m0, s7
	v_lshl_add_u64 v[246:247], s[2:3], 0, v[140:141]
	global_load_lds_dwordx4 v176, s[76:77]
	s_add_i32 m0, s7, 0x2000
	v_lshl_add_u64 v[248:249], s[2:3], 0, v[142:143]
	global_load_lds_dwordx4 v0, s[76:77]
	s_mov_b32 m0, s49
	v_lshl_add_u64 v[238:239], s[76:77], 0, v[176:177]
	global_load_lds_dwordx4 v[246:247], off
	s_mov_b32 m0, s51
	v_lshl_add_u64 v[176:177], s[76:77], 0, v[0:1]
	global_load_lds_dwordx4 v[248:249], off
	s_waitcnt vmcnt(8)
	s_waitcnt lgkmcnt(0)
	s_barrier
	s_setprio 1
	v_mfma_f32_16x16x32_bf16 v[62:65], v[134:137], v[182:185], v[62:65]
	v_mfma_f32_16x16x32_bf16 v[58:61], v[152:155], v[182:185], v[58:61]
	v_mfma_f32_16x16x32_bf16 v[54:57], v[134:137], v[190:193], v[54:57]
	v_mfma_f32_16x16x32_bf16 v[50:53], v[152:155], v[190:193], v[50:53]
	v_mfma_f32_16x16x32_bf16 v[46:49], v[134:137], v[198:201], v[46:49]
	v_mfma_f32_16x16x32_bf16 v[42:45], v[152:155], v[198:201], v[42:45]
	v_mfma_f32_16x16x32_bf16 v[38:41], v[134:137], v[206:209], v[38:41]
	v_mfma_f32_16x16x32_bf16 v[34:37], v[152:155], v[206:209], v[34:37]
	v_mfma_f32_16x16x32_bf16 v[62:65], v[148:151], v[186:189], v[62:65]
	v_mfma_f32_16x16x32_bf16 v[58:61], v[156:159], v[186:189], v[58:61]
	v_mfma_f32_16x16x32_bf16 v[54:57], v[148:151], v[194:197], v[54:57]
	v_mfma_f32_16x16x32_bf16 v[50:53], v[156:159], v[194:197], v[50:53]
	v_mfma_f32_16x16x32_bf16 v[46:49], v[148:151], v[202:205], v[46:49]
	v_mfma_f32_16x16x32_bf16 v[42:45], v[156:159], v[202:205], v[42:45]
	v_mfma_f32_16x16x32_bf16 v[38:41], v[148:151], v[210:213], v[38:41]
	v_mfma_f32_16x16x32_bf16 v[34:37], v[156:159], v[210:213], v[34:37]
	v_mfma_f32_16x16x32_bf16 v[30:33], v[160:163], v[182:185], v[30:33]
	v_mfma_f32_16x16x32_bf16 v[26:29], v[168:171], v[182:185], v[26:29]
	v_mfma_f32_16x16x32_bf16 v[22:25], v[160:163], v[190:193], v[22:25]
	v_mfma_f32_16x16x32_bf16 v[18:21], v[168:171], v[190:193], v[18:21]
	v_mfma_f32_16x16x32_bf16 v[14:17], v[160:163], v[198:201], v[14:17]
	v_mfma_f32_16x16x32_bf16 v[10:13], v[168:171], v[198:201], v[10:13]
	v_mfma_f32_16x16x32_bf16 v[6:9], v[160:163], v[206:209], v[6:9]
	v_mfma_f32_16x16x32_bf16 v[2:5], v[168:171], v[206:209], v[2:5]
	v_mfma_f32_16x16x32_bf16 v[30:33], v[164:167], v[186:189], v[30:33]
	v_mfma_f32_16x16x32_bf16 v[26:29], v[172:175], v[186:189], v[26:29]
	v_mfma_f32_16x16x32_bf16 v[22:25], v[164:167], v[194:197], v[22:25]
	v_mfma_f32_16x16x32_bf16 v[18:21], v[172:175], v[194:197], v[18:21]
	v_mfma_f32_16x16x32_bf16 v[14:17], v[164:167], v[202:205], v[14:17]
	v_mfma_f32_16x16x32_bf16 v[10:13], v[172:175], v[202:205], v[10:13]
	v_mfma_f32_16x16x32_bf16 v[6:9], v[164:167], v[210:213], v[6:9]
	v_mfma_f32_16x16x32_bf16 v[2:5], v[172:175], v[210:213], v[2:5]
	s_setprio 0
	s_barrier
	s_add_i32 s7, 0, 0x18000
	v_add_u32_e32 v0, s7, v180
	s_add_i32 s37, 0, 0x1c000
	ds_read_b128 v[134:137], v0
	ds_read_b128 v[148:151], v0 offset:1024
	ds_read_b128 v[152:155], v0 offset:2048
	ds_read_b128 v[156:159], v0 offset:3072
	v_add_u32_e32 v0, s37, v180
	ds_read_b128 v[160:163], v0
	ds_read_b128 v[164:167], v0 offset:1024
	ds_read_b128 v[168:171], v0 offset:2048
	ds_read_b128 v[172:175], v0 offset:3072
	s_add_u32 s2, s2, 0x40000
	s_addc_u32 s3, s3, 0
	s_mov_b32 m0, s52
	v_lshl_add_u64 v[244:245], s[2:3], 0, v[140:141]
	ds_read_b128 v[182:185], v181 offset:32768
	ds_read_b128 v[186:189], v181 offset:33792
	ds_read_b128 v[190:193], v181 offset:34816
	ds_read_b128 v[194:197], v181 offset:35840
	ds_read_b128 v[198:201], v181 offset:36864
	ds_read_b128 v[202:205], v181 offset:37888
	ds_read_b128 v[206:209], v181 offset:38912
	ds_read_b128 v[210:213], v181 offset:39936
	global_load_lds_dwordx4 v[244:245], off
	v_lshl_add_u64 v[244:245], s[2:3], 0, v[142:143]
	s_mov_b32 m0, s53
	s_nop 0
	global_load_lds_dwordx4 v[244:245], off
	s_waitcnt vmcnt(8)
	s_waitcnt lgkmcnt(0)
	s_barrier
	s_setprio 1
	v_mfma_f32_16x16x32_bf16 v[126:129], v[134:137], v[182:185], v[126:129]
	v_mfma_f32_16x16x32_bf16 v[122:125], v[152:155], v[182:185], v[122:125]
	v_mfma_f32_16x16x32_bf16 v[118:121], v[134:137], v[190:193], v[118:121]
	v_mfma_f32_16x16x32_bf16 v[114:117], v[152:155], v[190:193], v[114:117]
	v_mfma_f32_16x16x32_bf16 v[110:113], v[134:137], v[198:201], v[110:113]
	v_mfma_f32_16x16x32_bf16 v[106:109], v[152:155], v[198:201], v[106:109]
	v_mfma_f32_16x16x32_bf16 v[102:105], v[134:137], v[206:209], v[102:105]
	v_mfma_f32_16x16x32_bf16 v[98:101], v[152:155], v[206:209], v[98:101]
	v_mfma_f32_16x16x32_bf16 v[126:129], v[148:151], v[186:189], v[126:129]
	v_mfma_f32_16x16x32_bf16 v[122:125], v[156:159], v[186:189], v[122:125]
	v_mfma_f32_16x16x32_bf16 v[118:121], v[148:151], v[194:197], v[118:121]
	v_mfma_f32_16x16x32_bf16 v[114:117], v[156:159], v[194:197], v[114:117]
	v_mfma_f32_16x16x32_bf16 v[110:113], v[148:151], v[202:205], v[110:113]
	v_mfma_f32_16x16x32_bf16 v[106:109], v[156:159], v[202:205], v[106:109]
	v_mfma_f32_16x16x32_bf16 v[102:105], v[148:151], v[210:213], v[102:105]
	v_mfma_f32_16x16x32_bf16 v[98:101], v[156:159], v[210:213], v[98:101]
	v_mfma_f32_16x16x32_bf16 v[94:97], v[160:163], v[182:185], v[94:97]
	v_mfma_f32_16x16x32_bf16 v[90:93], v[168:171], v[182:185], v[90:93]
	v_mfma_f32_16x16x32_bf16 v[86:89], v[160:163], v[190:193], v[86:89]
	v_mfma_f32_16x16x32_bf16 v[82:85], v[168:171], v[190:193], v[82:85]
	v_mfma_f32_16x16x32_bf16 v[78:81], v[160:163], v[198:201], v[78:81]
	v_mfma_f32_16x16x32_bf16 v[74:77], v[168:171], v[198:201], v[74:77]
	v_mfma_f32_16x16x32_bf16 v[70:73], v[160:163], v[206:209], v[70:73]
	v_mfma_f32_16x16x32_bf16 v[66:69], v[168:171], v[206:209], v[66:69]
	v_mfma_f32_16x16x32_bf16 v[94:97], v[164:167], v[186:189], v[94:97]
	v_mfma_f32_16x16x32_bf16 v[90:93], v[172:175], v[186:189], v[90:93]
	v_mfma_f32_16x16x32_bf16 v[86:89], v[164:167], v[194:197], v[86:89]
	v_mfma_f32_16x16x32_bf16 v[82:85], v[172:175], v[194:197], v[82:85]
	v_mfma_f32_16x16x32_bf16 v[78:81], v[164:167], v[202:205], v[78:81]
	v_mfma_f32_16x16x32_bf16 v[74:77], v[172:175], v[202:205], v[74:77]
	v_mfma_f32_16x16x32_bf16 v[70:73], v[164:167], v[210:213], v[70:73]
	v_mfma_f32_16x16x32_bf16 v[66:69], v[172:175], v[210:213], v[66:69]
	s_setprio 0
	s_barrier
	s_add_i32 s2, s7, s48
	v_lshl_add_u64 v[214:215], v[214:215], 0, s[42:43]
	s_mov_b32 m0, s2
	ds_read_b128 v[182:185], v181 offset:49152
	ds_read_b128 v[186:189], v181 offset:50176
	ds_read_b128 v[190:193], v181 offset:51200
	ds_read_b128 v[194:197], v181 offset:52224
	ds_read_b128 v[198:201], v181 offset:53248
	ds_read_b128 v[202:205], v181 offset:54272
	ds_read_b128 v[206:209], v181 offset:55296
	ds_read_b128 v[210:213], v181 offset:56320
	global_load_lds_dwordx4 v[214:215], off
	v_lshl_add_u64 v[214:215], v[236:237], 0, s[42:43]
	s_add_i32 m0, s2, 0x2000
	s_add_i32 s2, s37, s48
	global_load_lds_dwordx4 v[214:215], off
	v_lshl_add_u64 v[214:215], v[238:239], 0, s[42:43]
	s_mov_b32 m0, s2
	v_lshl_add_u64 v[176:177], v[176:177], 0, s[42:43]
	global_load_lds_dwordx4 v[214:215], off
	s_add_i32 m0, s2, 0x2000
	s_nop 0
	global_load_lds_dwordx4 v[176:177], off
	v_lshl_add_u64 v[176:177], v[246:247], 0, s[42:43]
	s_mov_b32 m0, s56
	s_nop 0
	global_load_lds_dwordx4 v[176:177], off
	v_lshl_add_u64 v[176:177], v[248:249], 0, s[42:43]
	s_mov_b32 m0, s57
	s_nop 0
	global_load_lds_dwordx4 v[176:177], off
	s_waitcnt vmcnt(8)
	s_waitcnt lgkmcnt(0)
	s_barrier
	s_setprio 1
	v_mfma_f32_16x16x32_bf16 v[62:65], v[134:137], v[182:185], v[62:65]
	v_mfma_f32_16x16x32_bf16 v[58:61], v[152:155], v[182:185], v[58:61]
	v_mfma_f32_16x16x32_bf16 v[54:57], v[134:137], v[190:193], v[54:57]
	v_mfma_f32_16x16x32_bf16 v[50:53], v[152:155], v[190:193], v[50:53]
	v_mfma_f32_16x16x32_bf16 v[46:49], v[134:137], v[198:201], v[46:49]
	v_mfma_f32_16x16x32_bf16 v[42:45], v[152:155], v[198:201], v[42:45]
	v_mfma_f32_16x16x32_bf16 v[38:41], v[134:137], v[206:209], v[38:41]
	v_mfma_f32_16x16x32_bf16 v[34:37], v[152:155], v[206:209], v[34:37]
	v_mfma_f32_16x16x32_bf16 v[62:65], v[148:151], v[186:189], v[62:65]
	v_mfma_f32_16x16x32_bf16 v[58:61], v[156:159], v[186:189], v[58:61]
	v_mfma_f32_16x16x32_bf16 v[54:57], v[148:151], v[194:197], v[54:57]
	v_mfma_f32_16x16x32_bf16 v[50:53], v[156:159], v[194:197], v[50:53]
	v_mfma_f32_16x16x32_bf16 v[46:49], v[148:151], v[202:205], v[46:49]
	v_mfma_f32_16x16x32_bf16 v[42:45], v[156:159], v[202:205], v[42:45]
	v_mfma_f32_16x16x32_bf16 v[38:41], v[148:151], v[210:213], v[38:41]
	v_mfma_f32_16x16x32_bf16 v[34:37], v[156:159], v[210:213], v[34:37]
	v_mfma_f32_16x16x32_bf16 v[30:33], v[160:163], v[182:185], v[30:33]
	v_mfma_f32_16x16x32_bf16 v[26:29], v[168:171], v[182:185], v[26:29]
	v_mfma_f32_16x16x32_bf16 v[22:25], v[160:163], v[190:193], v[22:25]
	v_mfma_f32_16x16x32_bf16 v[18:21], v[168:171], v[190:193], v[18:21]
	v_mfma_f32_16x16x32_bf16 v[14:17], v[160:163], v[198:201], v[14:17]
	v_mfma_f32_16x16x32_bf16 v[10:13], v[168:171], v[198:201], v[10:13]
	v_mfma_f32_16x16x32_bf16 v[6:9], v[160:163], v[206:209], v[6:9]
	v_mfma_f32_16x16x32_bf16 v[2:5], v[168:171], v[206:209], v[2:5]
	v_mfma_f32_16x16x32_bf16 v[30:33], v[164:167], v[186:189], v[30:33]
	v_mfma_f32_16x16x32_bf16 v[26:29], v[172:175], v[186:189], v[26:29]
	v_mfma_f32_16x16x32_bf16 v[22:25], v[164:167], v[194:197], v[22:25]
	v_mfma_f32_16x16x32_bf16 v[18:21], v[172:175], v[194:197], v[18:21]
	v_mfma_f32_16x16x32_bf16 v[14:17], v[164:167], v[202:205], v[14:17]
	v_mfma_f32_16x16x32_bf16 v[10:13], v[172:175], v[202:205], v[10:13]
	v_mfma_f32_16x16x32_bf16 v[6:9], v[164:167], v[210:213], v[6:9]
	v_mfma_f32_16x16x32_bf16 v[2:5], v[172:175], v[210:213], v[2:5]
	s_setprio 0
	s_barrier
	s_add_i32 s6, s6, 2
	s_add_u32 s0, s0, 0x100
	s_addc_u32 s1, s1, 0
	s_cmp_gt_u32 s6, 13
	s_cbranch_scc0 .LBB0_1026
.Lkp_exit_win:
	s_and_b64 vcc, exec, s[18:19]
	s_cbranch_vccz .LBB0_1029
	s_barrier
.LBB0_1029:
	v_readlane_b32 s0, v251, 1
	v_readlane_b32 s1, v251, 2
	s_mul_hi_i32 s1, s40, s0
	s_mul_i32 s0, s40, s0
	v_readlane_b32 s2, v251, 0
	s_add_u32 s0, s0, s2
	v_readlane_b32 s2, v251, 7
	s_addc_u32 s1, s1, s2
	v_mov_b64_e32 v[130:131], s[12:13]
	v_cmp_ge_i64_e32 vcc, s[0:1], v[130:131]
	s_cbranch_vccnz .LBB0_1050
	s_ashr_i32 s1, s0, 31
	s_lshr_b32 s1, s1, 29
	s_add_i32 s1, s0, s1
	s_ashr_i32 s2, s1, 3
	s_and_b32 s1, s1, -8
	s_sub_i32 s0, s0, s1
	s_lshr_b32 s1, s0, 31
	s_or_b32 s1, s1, s63
	s_mul_i32 s6, s1, s0
	s_add_i32 s6, s6, s2
	s_cmpk_lt_i32 s6, 0x6c0
	s_mov_b64 s[0:1], -1
	s_cbranch_scc0 .LBB0_1044
	s_cmpk_gt_i32 s6, 0x5ff
	s_cbranch_scc0 .LBB0_1033
	s_add_i32 s0, s6, 0xfffffa00
	s_lshr_b32 s70, s0, 6
	s_and_b32 s69, s6, 63
	s_mov_b64 s[0:1], 0
